# CMP2: weight fill rewritten (only this workgroup's 32 KB slab, four 16-byte loads per thread, overlapped with the H-row loads)
# speedup vs baseline: 1.0151x; 1.0088x over previous
.LBB0_1188:
	s_cmp_lt_i32 s46, 10
	s_cselect_b64 s[2:3], -1, 0
	s_and_b64 s[2:3], s[2:3], s[0:1]
	s_andn2_b64 vcc, exec, s[2:3]
	s_cbranch_vccnz .LBB0_1205
	v_lshrrev_b32_e32 v200, 6, v188
	v_and_b32_e32 v201, 15, v188
	v_bfe_u32 v202, v188, 4, 2
	v_lshl_add_u32 v203, v200, 4, v201
	s_lshl_b32 s0, s33, 7
	v_add_u32_e32 v203, s0, v203
	v_lshlrev_b32_e32 v204, 9, v203
	v_lshl_add_u32 v204, v202, 7, v204
	s_add_u32 s0, s44, 0x36040000
	s_addc_u32 s1, s45, 0
	v_readlane_b32 s12, v235, 45
	v_readlane_b32 s13, v235, 46
	s_lshr_b32 s15, s33, 7
	s_lshl_b32 s15, s15, 15
	s_add_u32 s12, s12, s15
	s_addc_u32 s13, s13, 0
	v_lshlrev_b32_e32 v210, 4, v188
	v_add_u32_e32 v211, 0x2000, v210
	v_add_u32_e32 v212, 0x4000, v210
	v_add_u32_e32 v213, 0x6000, v210
	v_add_u32_e32 v214, s15, v210
	global_load_dwordx4 v[0:3], v210, s[12:13]
	global_load_dwordx4 v[4:7], v211, s[12:13]
	global_load_dwordx4 v[8:11], v212, s[12:13]
	global_load_dwordx4 v[12:15], v213, s[12:13]
	global_load_dwordx4 v[100:103], v204, s[0:1]
	global_load_dwordx4 v[104:107], v204, s[0:1] offset:16
	global_load_dwordx4 v[108:111], v204, s[0:1] offset:32
	global_load_dwordx4 v[112:115], v204, s[0:1] offset:48
	global_load_dwordx4 v[116:119], v204, s[0:1] offset:64
	global_load_dwordx4 v[120:123], v204, s[0:1] offset:80
	global_load_dwordx4 v[124:127], v204, s[0:1] offset:96
	global_load_dwordx4 v[128:131], v204, s[0:1] offset:112
	s_waitcnt vmcnt(8)
	ds_write_b128 v214, v[0:3]
	ds_write_b128 v214, v[4:7] offset:8192
	ds_write_b128 v214, v[8:11] offset:16384
	ds_write_b128 v214, v[12:15] offset:24576
.LBB0_1197:
	s_waitcnt lgkmcnt(0)
	s_barrier
	s_mov_b64 s[4:5], exec
	s_lshr_b32 s0, s33, 7
	s_lshl_b32 s0, s0, 15
	v_lshlrev_b32_e32 v206, 13, v202
	v_lshl_add_u32 v206, v201, 2, v206
	v_add_u32_e32 v206, s0, v206
	v_mov_b64_e32 v[132:133], 0
	v_mov_b64_e32 v[134:135], 0
	v_mov_b64_e32 v[136:137], 0
	v_mov_b64_e32 v[138:139], 0
	v_mov_b64_e32 v[140:141], 0
	v_mov_b64_e32 v[142:143], 0
	v_mov_b64_e32 v[144:145], 0
	v_mov_b64_e32 v[146:147], 0
	ds_read_b32 v148, v206 offset:0
	ds_read_b32 v149, v206 offset:64
	ds_read_b32 v150, v206 offset:128
	ds_read_b32 v151, v206 offset:192
	ds_read_b32 v152, v206 offset:256
	ds_read_b32 v153, v206 offset:320
	ds_read_b32 v154, v206 offset:384
	ds_read_b32 v155, v206 offset:448
	ds_read_b32 v156, v206 offset:512
	ds_read_b32 v157, v206 offset:576
	ds_read_b32 v158, v206 offset:640
	ds_read_b32 v159, v206 offset:704
	s_waitcnt vmcnt(0)
	ds_read_b32 v160, v206 offset:768
	ds_read_b32 v161, v206 offset:832
	ds_read_b32 v162, v206 offset:896
	ds_read_b32 v163, v206 offset:960
	s_waitcnt lgkmcnt(12)
	v_mfma_f32_16x16x4_f32 v[132:135], v100, v148, v[132:135]
	v_mfma_f32_16x16x4_f32 v[136:139], v100, v149, v[136:139]
	v_mfma_f32_16x16x4_f32 v[140:143], v100, v150, v[140:143]
	v_mfma_f32_16x16x4_f32 v[144:147], v100, v151, v[144:147]
	ds_read_b32 v148, v206 offset:1024
	ds_read_b32 v149, v206 offset:1088
	ds_read_b32 v150, v206 offset:1152
	ds_read_b32 v151, v206 offset:1216
	s_waitcnt lgkmcnt(12)
	v_mfma_f32_16x16x4_f32 v[132:135], v101, v152, v[132:135]
	v_mfma_f32_16x16x4_f32 v[136:139], v101, v153, v[136:139]
	v_mfma_f32_16x16x4_f32 v[140:143], v101, v154, v[140:143]
	v_mfma_f32_16x16x4_f32 v[144:147], v101, v155, v[144:147]
	ds_read_b32 v152, v206 offset:1280
	ds_read_b32 v153, v206 offset:1344
	ds_read_b32 v154, v206 offset:1408
	ds_read_b32 v155, v206 offset:1472
	s_waitcnt lgkmcnt(12)
	v_mfma_f32_16x16x4_f32 v[132:135], v102, v156, v[132:135]
	v_mfma_f32_16x16x4_f32 v[136:139], v102, v157, v[136:139]
	v_mfma_f32_16x16x4_f32 v[140:143], v102, v158, v[140:143]
	v_mfma_f32_16x16x4_f32 v[144:147], v102, v159, v[144:147]
	ds_read_b32 v156, v206 offset:1536
	ds_read_b32 v157, v206 offset:1600
	ds_read_b32 v158, v206 offset:1664
	ds_read_b32 v159, v206 offset:1728
	s_waitcnt lgkmcnt(12)
	v_mfma_f32_16x16x4_f32 v[132:135], v103, v160, v[132:135]
	v_mfma_f32_16x16x4_f32 v[136:139], v103, v161, v[136:139]
	v_mfma_f32_16x16x4_f32 v[140:143], v103, v162, v[140:143]
	v_mfma_f32_16x16x4_f32 v[144:147], v103, v163, v[144:147]
	ds_read_b32 v160, v206 offset:1792
	ds_read_b32 v161, v206 offset:1856
	ds_read_b32 v162, v206 offset:1920
	ds_read_b32 v163, v206 offset:1984
	s_waitcnt lgkmcnt(12)
	v_mfma_f32_16x16x4_f32 v[132:135], v104, v148, v[132:135]
	v_mfma_f32_16x16x4_f32 v[136:139], v104, v149, v[136:139]
	v_mfma_f32_16x16x4_f32 v[140:143], v104, v150, v[140:143]
	v_mfma_f32_16x16x4_f32 v[144:147], v104, v151, v[144:147]
	ds_read_b32 v148, v206 offset:2048
	ds_read_b32 v149, v206 offset:2112
	ds_read_b32 v150, v206 offset:2176
	ds_read_b32 v151, v206 offset:2240
	s_waitcnt lgkmcnt(12)
	v_mfma_f32_16x16x4_f32 v[132:135], v105, v152, v[132:135]
	v_mfma_f32_16x16x4_f32 v[136:139], v105, v153, v[136:139]
	v_mfma_f32_16x16x4_f32 v[140:143], v105, v154, v[140:143]
	v_mfma_f32_16x16x4_f32 v[144:147], v105, v155, v[144:147]
	ds_read_b32 v152, v206 offset:2304
	ds_read_b32 v153, v206 offset:2368
	ds_read_b32 v154, v206 offset:2432
	ds_read_b32 v155, v206 offset:2496
	s_waitcnt lgkmcnt(12)
	v_mfma_f32_16x16x4_f32 v[132:135], v106, v156, v[132:135]
	v_mfma_f32_16x16x4_f32 v[136:139], v106, v157, v[136:139]
	v_mfma_f32_16x16x4_f32 v[140:143], v106, v158, v[140:143]
	v_mfma_f32_16x16x4_f32 v[144:147], v106, v159, v[144:147]
	ds_read_b32 v156, v206 offset:2560
	ds_read_b32 v157, v206 offset:2624
	ds_read_b32 v158, v206 offset:2688
	ds_read_b32 v159, v206 offset:2752
	s_waitcnt lgkmcnt(12)
	v_mfma_f32_16x16x4_f32 v[132:135], v107, v160, v[132:135]
	v_mfma_f32_16x16x4_f32 v[136:139], v107, v161, v[136:139]
	v_mfma_f32_16x16x4_f32 v[140:143], v107, v162, v[140:143]
	v_mfma_f32_16x16x4_f32 v[144:147], v107, v163, v[144:147]
	ds_read_b32 v160, v206 offset:2816
	ds_read_b32 v161, v206 offset:2880
	ds_read_b32 v162, v206 offset:2944
	ds_read_b32 v163, v206 offset:3008
	s_waitcnt lgkmcnt(12)
	v_mfma_f32_16x16x4_f32 v[132:135], v108, v148, v[132:135]
	v_mfma_f32_16x16x4_f32 v[136:139], v108, v149, v[136:139]
	v_mfma_f32_16x16x4_f32 v[140:143], v108, v150, v[140:143]
	v_mfma_f32_16x16x4_f32 v[144:147], v108, v151, v[144:147]
	ds_read_b32 v148, v206 offset:3072
	ds_read_b32 v149, v206 offset:3136
	ds_read_b32 v150, v206 offset:3200
	ds_read_b32 v151, v206 offset:3264
	s_waitcnt lgkmcnt(12)
	v_mfma_f32_16x16x4_f32 v[132:135], v109, v152, v[132:135]
	v_mfma_f32_16x16x4_f32 v[136:139], v109, v153, v[136:139]
	v_mfma_f32_16x16x4_f32 v[140:143], v109, v154, v[140:143]
	v_mfma_f32_16x16x4_f32 v[144:147], v109, v155, v[144:147]
	ds_read_b32 v152, v206 offset:3328
	ds_read_b32 v153, v206 offset:3392
	ds_read_b32 v154, v206 offset:3456
	ds_read_b32 v155, v206 offset:3520
	s_waitcnt lgkmcnt(12)
	v_mfma_f32_16x16x4_f32 v[132:135], v110, v156, v[132:135]
	v_mfma_f32_16x16x4_f32 v[136:139], v110, v157, v[136:139]
	v_mfma_f32_16x16x4_f32 v[140:143], v110, v158, v[140:143]
	v_mfma_f32_16x16x4_f32 v[144:147], v110, v159, v[144:147]
	ds_read_b32 v156, v206 offset:3584
	ds_read_b32 v157, v206 offset:3648
	ds_read_b32 v158, v206 offset:3712
	ds_read_b32 v159, v206 offset:3776
	s_waitcnt lgkmcnt(12)
	v_mfma_f32_16x16x4_f32 v[132:135], v111, v160, v[132:135]
	v_mfma_f32_16x16x4_f32 v[136:139], v111, v161, v[136:139]
	v_mfma_f32_16x16x4_f32 v[140:143], v111, v162, v[140:143]
	v_mfma_f32_16x16x4_f32 v[144:147], v111, v163, v[144:147]
	ds_read_b32 v160, v206 offset:3840
	ds_read_b32 v161, v206 offset:3904
	ds_read_b32 v162, v206 offset:3968
	ds_read_b32 v163, v206 offset:4032
	s_waitcnt lgkmcnt(12)
	v_mfma_f32_16x16x4_f32 v[132:135], v112, v148, v[132:135]
	v_mfma_f32_16x16x4_f32 v[136:139], v112, v149, v[136:139]
	v_mfma_f32_16x16x4_f32 v[140:143], v112, v150, v[140:143]
	v_mfma_f32_16x16x4_f32 v[144:147], v112, v151, v[144:147]
	ds_read_b32 v148, v206 offset:4096
	ds_read_b32 v149, v206 offset:4160
	ds_read_b32 v150, v206 offset:4224
	ds_read_b32 v151, v206 offset:4288
	s_waitcnt lgkmcnt(12)
	v_mfma_f32_16x16x4_f32 v[132:135], v113, v152, v[132:135]
	v_mfma_f32_16x16x4_f32 v[136:139], v113, v153, v[136:139]
	v_mfma_f32_16x16x4_f32 v[140:143], v113, v154, v[140:143]
	v_mfma_f32_16x16x4_f32 v[144:147], v113, v155, v[144:147]
	ds_read_b32 v152, v206 offset:4352
	ds_read_b32 v153, v206 offset:4416
	ds_read_b32 v154, v206 offset:4480
	ds_read_b32 v155, v206 offset:4544
	s_waitcnt lgkmcnt(12)
	v_mfma_f32_16x16x4_f32 v[132:135], v114, v156, v[132:135]
	v_mfma_f32_16x16x4_f32 v[136:139], v114, v157, v[136:139]
	v_mfma_f32_16x16x4_f32 v[140:143], v114, v158, v[140:143]
	v_mfma_f32_16x16x4_f32 v[144:147], v114, v159, v[144:147]
	ds_read_b32 v156, v206 offset:4608
	ds_read_b32 v157, v206 offset:4672
	ds_read_b32 v158, v206 offset:4736
	ds_read_b32 v159, v206 offset:4800
	s_waitcnt lgkmcnt(12)
	v_mfma_f32_16x16x4_f32 v[132:135], v115, v160, v[132:135]
	v_mfma_f32_16x16x4_f32 v[136:139], v115, v161, v[136:139]
	v_mfma_f32_16x16x4_f32 v[140:143], v115, v162, v[140:143]
	v_mfma_f32_16x16x4_f32 v[144:147], v115, v163, v[144:147]
	ds_read_b32 v160, v206 offset:4864
	ds_read_b32 v161, v206 offset:4928
	ds_read_b32 v162, v206 offset:4992
	ds_read_b32 v163, v206 offset:5056
	s_waitcnt lgkmcnt(12)
	v_mfma_f32_16x16x4_f32 v[132:135], v116, v148, v[132:135]
	v_mfma_f32_16x16x4_f32 v[136:139], v116, v149, v[136:139]
	v_mfma_f32_16x16x4_f32 v[140:143], v116, v150, v[140:143]
	v_mfma_f32_16x16x4_f32 v[144:147], v116, v151, v[144:147]
	ds_read_b32 v148, v206 offset:5120
	ds_read_b32 v149, v206 offset:5184
	ds_read_b32 v150, v206 offset:5248
	ds_read_b32 v151, v206 offset:5312
	s_waitcnt lgkmcnt(12)
	v_mfma_f32_16x16x4_f32 v[132:135], v117, v152, v[132:135]
	v_mfma_f32_16x16x4_f32 v[136:139], v117, v153, v[136:139]
	v_mfma_f32_16x16x4_f32 v[140:143], v117, v154, v[140:143]
	v_mfma_f32_16x16x4_f32 v[144:147], v117, v155, v[144:147]
	ds_read_b32 v152, v206 offset:5376
	ds_read_b32 v153, v206 offset:5440
	ds_read_b32 v154, v206 offset:5504
	ds_read_b32 v155, v206 offset:5568
	s_waitcnt lgkmcnt(12)
	v_mfma_f32_16x16x4_f32 v[132:135], v118, v156, v[132:135]
	v_mfma_f32_16x16x4_f32 v[136:139], v118, v157, v[136:139]
	v_mfma_f32_16x16x4_f32 v[140:143], v118, v158, v[140:143]
	v_mfma_f32_16x16x4_f32 v[144:147], v118, v159, v[144:147]
	ds_read_b32 v156, v206 offset:5632
	ds_read_b32 v157, v206 offset:5696
	ds_read_b32 v158, v206 offset:5760
	ds_read_b32 v159, v206 offset:5824
	s_waitcnt lgkmcnt(12)
	v_mfma_f32_16x16x4_f32 v[132:135], v119, v160, v[132:135]
	v_mfma_f32_16x16x4_f32 v[136:139], v119, v161, v[136:139]
	v_mfma_f32_16x16x4_f32 v[140:143], v119, v162, v[140:143]
	v_mfma_f32_16x16x4_f32 v[144:147], v119, v163, v[144:147]
	ds_read_b32 v160, v206 offset:5888
	ds_read_b32 v161, v206 offset:5952
	ds_read_b32 v162, v206 offset:6016
	ds_read_b32 v163, v206 offset:6080
	s_waitcnt lgkmcnt(12)
	v_mfma_f32_16x16x4_f32 v[132:135], v120, v148, v[132:135]
	v_mfma_f32_16x16x4_f32 v[136:139], v120, v149, v[136:139]
	v_mfma_f32_16x16x4_f32 v[140:143], v120, v150, v[140:143]
	v_mfma_f32_16x16x4_f32 v[144:147], v120, v151, v[144:147]
	ds_read_b32 v148, v206 offset:6144
	ds_read_b32 v149, v206 offset:6208
	ds_read_b32 v150, v206 offset:6272
	ds_read_b32 v151, v206 offset:6336
	s_waitcnt lgkmcnt(12)
	v_mfma_f32_16x16x4_f32 v[132:135], v121, v152, v[132:135]
	v_mfma_f32_16x16x4_f32 v[136:139], v121, v153, v[136:139]
	v_mfma_f32_16x16x4_f32 v[140:143], v121, v154, v[140:143]
	v_mfma_f32_16x16x4_f32 v[144:147], v121, v155, v[144:147]
	ds_read_b32 v152, v206 offset:6400
	ds_read_b32 v153, v206 offset:6464
	ds_read_b32 v154, v206 offset:6528
	ds_read_b32 v155, v206 offset:6592
	s_waitcnt lgkmcnt(12)
	v_mfma_f32_16x16x4_f32 v[132:135], v122, v156, v[132:135]
	v_mfma_f32_16x16x4_f32 v[136:139], v122, v157, v[136:139]
	v_mfma_f32_16x16x4_f32 v[140:143], v122, v158, v[140:143]
	v_mfma_f32_16x16x4_f32 v[144:147], v122, v159, v[144:147]
	ds_read_b32 v156, v206 offset:6656
	ds_read_b32 v157, v206 offset:6720
	ds_read_b32 v158, v206 offset:6784
	ds_read_b32 v159, v206 offset:6848
	s_waitcnt lgkmcnt(12)
	v_mfma_f32_16x16x4_f32 v[132:135], v123, v160, v[132:135]
	v_mfma_f32_16x16x4_f32 v[136:139], v123, v161, v[136:139]
	v_mfma_f32_16x16x4_f32 v[140:143], v123, v162, v[140:143]
	v_mfma_f32_16x16x4_f32 v[144:147], v123, v163, v[144:147]
	ds_read_b32 v160, v206 offset:6912
	ds_read_b32 v161, v206 offset:6976
	ds_read_b32 v162, v206 offset:7040
	ds_read_b32 v163, v206 offset:7104
	s_waitcnt lgkmcnt(12)
	v_mfma_f32_16x16x4_f32 v[132:135], v124, v148, v[132:135]
	v_mfma_f32_16x16x4_f32 v[136:139], v124, v149, v[136:139]
	v_mfma_f32_16x16x4_f32 v[140:143], v124, v150, v[140:143]
	v_mfma_f32_16x16x4_f32 v[144:147], v124, v151, v[144:147]
	ds_read_b32 v148, v206 offset:7168
	ds_read_b32 v149, v206 offset:7232
	ds_read_b32 v150, v206 offset:7296
	ds_read_b32 v151, v206 offset:7360
	s_waitcnt lgkmcnt(12)
	v_mfma_f32_16x16x4_f32 v[132:135], v125, v152, v[132:135]
	v_mfma_f32_16x16x4_f32 v[136:139], v125, v153, v[136:139]
	v_mfma_f32_16x16x4_f32 v[140:143], v125, v154, v[140:143]
	v_mfma_f32_16x16x4_f32 v[144:147], v125, v155, v[144:147]
	ds_read_b32 v152, v206 offset:7424
	ds_read_b32 v153, v206 offset:7488
	ds_read_b32 v154, v206 offset:7552
	ds_read_b32 v155, v206 offset:7616
	s_waitcnt lgkmcnt(12)
	v_mfma_f32_16x16x4_f32 v[132:135], v126, v156, v[132:135]
	v_mfma_f32_16x16x4_f32 v[136:139], v126, v157, v[136:139]
	v_mfma_f32_16x16x4_f32 v[140:143], v126, v158, v[140:143]
	v_mfma_f32_16x16x4_f32 v[144:147], v126, v159, v[144:147]
	ds_read_b32 v156, v206 offset:7680
	ds_read_b32 v157, v206 offset:7744
	ds_read_b32 v158, v206 offset:7808
	ds_read_b32 v159, v206 offset:7872
	s_waitcnt lgkmcnt(12)
	v_mfma_f32_16x16x4_f32 v[132:135], v127, v160, v[132:135]
	v_mfma_f32_16x16x4_f32 v[136:139], v127, v161, v[136:139]
	v_mfma_f32_16x16x4_f32 v[140:143], v127, v162, v[140:143]
	v_mfma_f32_16x16x4_f32 v[144:147], v127, v163, v[144:147]
	ds_read_b32 v160, v206 offset:7936
	ds_read_b32 v161, v206 offset:8000
	ds_read_b32 v162, v206 offset:8064
	ds_read_b32 v163, v206 offset:8128
	s_waitcnt lgkmcnt(12)
	v_mfma_f32_16x16x4_f32 v[132:135], v128, v148, v[132:135]
	v_mfma_f32_16x16x4_f32 v[136:139], v128, v149, v[136:139]
	v_mfma_f32_16x16x4_f32 v[140:143], v128, v150, v[140:143]
	v_mfma_f32_16x16x4_f32 v[144:147], v128, v151, v[144:147]
	s_waitcnt lgkmcnt(8)
	v_mfma_f32_16x16x4_f32 v[132:135], v129, v152, v[132:135]
	v_mfma_f32_16x16x4_f32 v[136:139], v129, v153, v[136:139]
	v_mfma_f32_16x16x4_f32 v[140:143], v129, v154, v[140:143]
	v_mfma_f32_16x16x4_f32 v[144:147], v129, v155, v[144:147]
	s_waitcnt lgkmcnt(4)
	v_mfma_f32_16x16x4_f32 v[132:135], v130, v156, v[132:135]
	v_mfma_f32_16x16x4_f32 v[136:139], v130, v157, v[136:139]
	v_mfma_f32_16x16x4_f32 v[140:143], v130, v158, v[140:143]
	v_mfma_f32_16x16x4_f32 v[144:147], v130, v159, v[144:147]
	s_waitcnt lgkmcnt(0)
	v_mfma_f32_16x16x4_f32 v[132:135], v131, v160, v[132:135]
	v_mfma_f32_16x16x4_f32 v[136:139], v131, v161, v[136:139]
	v_mfma_f32_16x16x4_f32 v[140:143], v131, v162, v[140:143]
	v_mfma_f32_16x16x4_f32 v[144:147], v131, v163, v[144:147]
	s_nop 7
	s_nop 7
	s_nop 3
	s_movk_i32 s12, 0x7fff
	v_lshlrev_b32_e32 v207, 2, v202
	v_lshl_add_u32 v207, v200, 4, v207
	s_lshl_b32 s0, s33, 7
	v_add_u32_e32 v207, s0, v207
	v_and_b32_e32 v208, 0x1fc, v207
	s_movk_i32 s14, 0x1fc
	v_cmp_ne_u32_e32 vcc, s14, v208
	v_lshlrev_b32_e32 v207, 7, v207
	v_lshl_add_u32 v207, v201, 1, v207
	s_add_u32 s0, s44, 0x35c40000
	s_addc_u32 s1, s45, 0
	v_bfe_u32 v209, v132, 16, 1
	v_add3_u32 v132, v132, v209, s12
	v_lshrrev_b32_e32 v132, 16, v132
	v_cndmask_b32_e32 v132, 0, v132, vcc
	global_store_short v207, v132, s[0:1]
	v_bfe_u32 v209, v133, 16, 1
	v_add3_u32 v133, v133, v209, s12
	v_lshrrev_b32_e32 v133, 16, v133
	v_cndmask_b32_e32 v133, 0, v133, vcc
	global_store_short v207, v133, s[0:1] offset:128
	v_bfe_u32 v209, v134, 16, 1
	v_add3_u32 v134, v134, v209, s12
	v_lshrrev_b32_e32 v134, 16, v134
	v_cndmask_b32_e32 v134, 0, v134, vcc
	global_store_short v207, v134, s[0:1] offset:256
	v_bfe_u32 v209, v135, 16, 1
	v_add3_u32 v135, v135, v209, s12
	v_lshrrev_b32_e32 v135, 16, v135
	v_cndmask_b32_e32 v135, 0, v135, vcc
	global_store_short v207, v135, s[0:1] offset:384
	v_bfe_u32 v209, v136, 16, 1
	v_add3_u32 v136, v136, v209, s12
	v_lshrrev_b32_e32 v136, 16, v136
	v_cndmask_b32_e32 v136, 0, v136, vcc
	global_store_short v207, v136, s[0:1] offset:32
	v_bfe_u32 v209, v137, 16, 1
	v_add3_u32 v137, v137, v209, s12
	v_lshrrev_b32_e32 v137, 16, v137
	v_cndmask_b32_e32 v137, 0, v137, vcc
	global_store_short v207, v137, s[0:1] offset:160
	v_bfe_u32 v209, v138, 16, 1
	v_add3_u32 v138, v138, v209, s12
	v_lshrrev_b32_e32 v138, 16, v138
	v_cndmask_b32_e32 v138, 0, v138, vcc
	global_store_short v207, v138, s[0:1] offset:288
	v_bfe_u32 v209, v139, 16, 1
	v_add3_u32 v139, v139, v209, s12
	v_lshrrev_b32_e32 v139, 16, v139
	v_cndmask_b32_e32 v139, 0, v139, vcc
	global_store_short v207, v139, s[0:1] offset:416
	v_bfe_u32 v209, v140, 16, 1
	v_add3_u32 v140, v140, v209, s12
	v_lshrrev_b32_e32 v140, 16, v140
	v_cndmask_b32_e32 v140, 0, v140, vcc
	global_store_short v207, v140, s[0:1] offset:64
	v_bfe_u32 v209, v141, 16, 1
	v_add3_u32 v141, v141, v209, s12
	v_lshrrev_b32_e32 v141, 16, v141
	v_cndmask_b32_e32 v141, 0, v141, vcc
	global_store_short v207, v141, s[0:1] offset:192
	v_bfe_u32 v209, v142, 16, 1
	v_add3_u32 v142, v142, v209, s12
	v_lshrrev_b32_e32 v142, 16, v142
	v_cndmask_b32_e32 v142, 0, v142, vcc
	global_store_short v207, v142, s[0:1] offset:320
	v_bfe_u32 v209, v143, 16, 1
	v_add3_u32 v143, v143, v209, s12
	v_lshrrev_b32_e32 v143, 16, v143
	v_cndmask_b32_e32 v143, 0, v143, vcc
	global_store_short v207, v143, s[0:1] offset:448
	v_bfe_u32 v209, v144, 16, 1
	v_add3_u32 v144, v144, v209, s12
	v_lshrrev_b32_e32 v144, 16, v144
	v_cndmask_b32_e32 v144, 0, v144, vcc
	global_store_short v207, v144, s[0:1] offset:96
	v_bfe_u32 v209, v145, 16, 1
	v_add3_u32 v145, v145, v209, s12
	v_lshrrev_b32_e32 v145, 16, v145
	v_cndmask_b32_e32 v145, 0, v145, vcc
	global_store_short v207, v145, s[0:1] offset:224
	v_bfe_u32 v209, v146, 16, 1
	v_add3_u32 v146, v146, v209, s12
	v_lshrrev_b32_e32 v146, 16, v146
	v_cndmask_b32_e32 v146, 0, v146, vcc
	global_store_short v207, v146, s[0:1] offset:352
	v_bfe_u32 v209, v147, 16, 1
	v_add3_u32 v147, v147, v209, s12
	v_lshrrev_b32_e32 v147, 16, v147
	v_cndmask_b32_e32 v147, 0, v147, vcc
	global_store_short v207, v147, s[0:1] offset:480
